# P1 GEMM unit order: 4 row panels x 8 column tiles per XCD round (group size 4 instead of 2)
# speedup vs baseline: 1.0185x; 1.0185x over previous
; #define PG8_STAGE(bufoff, gbase, voff) do { _Pragma("unroll") for (int _i = 0; _i < 2; ++_i) \
;         __builtin_amdgcn_global_load_lds((const unsigned*)((const char*)(gbase) + (voff)[_i]), (LAS unsigned*)(lds + (bufoff) + ldsw + _i * 8192), 16, 0, 0); } while (0)
; #define PG8_WAIT_V(n) asm volatile("s_waitcnt vmcnt(" #n ")" ::: "memory")
; #define PG8_BAR __builtin_amdgcn_s_barrier()
;     __host__ __device__ bool next(int i, Unit& u) const {
;         const long L = (long)i * G + c; if (L >= nwg) return false;
;         int wgid = (int)L; { const int q = nwg / NXCD, r = nwg % NXCD, xcd = wgid % NXCD, off = wgid / NXCD; wgid = (xcd < r ? xcd * (q + 1) : r * (q + 1) + (xcd - r) * q) + off; }
;         const int nig = WGM * nN, gid = wgid / nig, fm = gid * WGM, gsz = (nM - fm) < WGM ? (nM - fm) : WGM;
;         u.pm = fm + ((wgid % nig) % gsz); u.pn = (wgid % nig) / gsz; return true;
;     }
; template <class Epi, class Sched>
; __device__ __forceinline__ void gemm_phase(LAS unsigned char* lds, const Gemm g, const Sched& S, const Epi& E) {
;     ...
;     Unit cur, nxt; int ui = 0;
;     if (!S.next(0, cur)) return;
;     f32x4 acc[2][2][4][2];
; #pragma unroll
;     for (int a = 0; a < 2; ++a)
; #pragma unroll
;         for (int b = 0; b < 2; ++b)
; #pragma unroll
;             for (int m = 0; m < 4; ++m)
; #pragma unroll
;                 for (int n = 0; n < 2; ++n) acc[a][b][m][n] = (f32x4){0.f, 0.f, 0.f, 0.f};
;     bf16x8 At[4][2], B0[2][2], B1[2][2];
;     const char* cA = (const char*)g.A + (size_t)cur.pm * tstepA; const char* cB = (const char*)g.Bt + (size_t)cur.pn * tstepB;
;     PG8_STAGE(PG8_SB(0, 0), cB, voffB); PG8_STAGE(PG8_SB(0, 1), cB + hstepB, voffB); PG8_STAGE(PG8_SA(0, 0), cA, voffA); PG8_STAGE(PG8_SA(0, 1), cA + hstepA, voffA);
;     if (wr == 1) PG8_BAR;
;     PG8_WAIT_V(2); PG8_BAR;
;     PG8_STAGE(PG8_SB(1, 0), cB + kstep, voffB); PG8_STAGE(PG8_SA(1, 0), cA + kstep, voffA); PG8_STAGE(PG8_SB(1, 1), cB + hstepB + kstep, voffB);
;     PG8_WAIT_V(6); PG8_BAR;
.LBB0_164:
	v_and_b32_e32 v0, 32, v188
	v_lshrrev_b32_e32 v1, 1, v188
	s_ashr_i32 s4, s7, 3
	v_bfe_u32 v8, v188, 2, 4
	v_bitop3_b32 v9, v45, v0, 48 bitop3:0x6c
	v_and_b32_e32 v10, 64, v188
	v_and_b32_e32 v1, 24, v1
	v_and_b32_e32 v2, 4, v47
	v_bfe_u32 v3, v188, 2, 2
	v_or_b32_e32 v0, v9, v10
	v_or3_b32 v1, v2, v3, v1
	v_or_b32_e32 v2, v42, v8
	s_movk_i32 s7, 0x60
	v_add_u32_e32 v11, 0x2000, v45
	s_add_i32 s4, s6, s4
	v_and_or_b32 v3, v46, s7, v1
	v_lshl_or_b32 v128, v2, 12, v0
	v_lshrrev_b32_e32 v2, 7, v11
	s_movk_i32 s7, 0xf0
	s_mul_hi_i32 s6, s4, 0xb21642c9
	v_lshl_or_b32 v130, v3, 12, v0
	v_and_or_b32 v3, v2, s7, v8
	s_movk_i32 s7, 0xe0
	s_add_i32 s6, s6, s4
	v_and_or_b32 v1, v2, s7, v1
	s_lshr_b32 s7, s6, 31
	s_ashr_i32 s6, s6, 7
	s_add_i32 s6, s6, s7
	s_lshl_b32 s13, s6, 2
	s_sub_i32 s7, 0x42, s13
	s_mulk_i32 s6, 0xb8
	s_min_u32 s15, s7, 4
	s_sub_i32 s16, s4, s6
	v_lshl_or_b32 v134, v1, 12, v0
	s_mov_b32 s4, s16
	v_cvt_f32_ubyte0_e32 v1, s15
	v_lshl_or_b32 v132, v3, 12, v0
	v_cvt_f32_i32_e32 v0, s4
	v_rcp_iflag_f32_e32 v2, v1
	s_lshr_b32 s12, s14, 6
	s_ashr_i32 s4, s4, 30
	s_lshr_b32 s5, s14, 8
	v_mul_f32_e32 v2, v0, v2
	v_trunc_f32_e32 v2, v2
	v_fma_f32 v0, -v2, v1, v0
	v_cvt_i32_f32_e32 v2, v2
	s_lshl_b32 s36, s12, 10
	s_or_b32 s4, s4, 1
	v_cmp_ge_f32_e64 s[6:7], |v0|, v1
	s_and_b64 s[6:7], s[6:7], exec
	s_cselect_b32 s4, s4, 0
	v_readfirstlane_b32 s6, v2
	s_add_i32 s4, s6, s4
	s_mul_i32 s6, s4, s15
	s_sub_i32 s6, s16, s6
	s_sext_i32_i8 s6, s6
	s_add_i32 s24, s13, s6
	s_ashr_i32 s25, s24, 31
	s_bfe_i64 s[16:17], s[4:5], 0x80000
	s_lshl_b64 s[6:7], s[24:25], 20
	s_lshl_b64 s[16:17], s[16:17], 20
	s_add_u32 s28, s8, s16
	s_addc_u32 s29, s9, s17
	s_add_i32 s25, s36, 0
	s_add_i32 m0, s25, 0x10000
	v_mov_b32_e32 v131, 0
	global_load_lds_dwordx4 v130, s[28:29]
	s_add_i32 m0, s25, 0x12000
	s_add_u32 s16, s28, 0x80000
	global_load_lds_dwordx4 v134, s[28:29]
	s_addc_u32 s17, s29, 0
	s_add_i32 m0, s25, 0x14000
	v_mov_b32_e32 v135, v131
	global_load_lds_dwordx4 v130, s[16:17]
	s_add_i32 m0, s25, 0x16000
	s_add_u32 s26, s10, s6
	s_addc_u32 s27, s11, s7
	s_add_i32 s37, s25, 0x2000
	global_load_lds_dwordx4 v134, s[16:17]
	s_mov_b32 m0, s25
	s_add_u32 s6, s26, 0x80000
	global_load_lds_dwordx4 v128, s[26:27]
	s_mov_b32 m0, s37
	s_addc_u32 s7, s27, 0
	s_add_i32 s38, s25, 0x4000
	global_load_lds_dwordx4 v132, s[26:27]
	s_mov_b32 m0, s38
	s_add_i32 s39, s25, 0x6000
	global_load_lds_dwordx4 v128, s[6:7]
	s_mov_b32 m0, s39
	v_mov_b32_e32 v129, v131
	global_load_lds_dwordx4 v132, s[6:7]
	v_mov_b32_e32 v133, v131
	s_cmp_eq_u32 s5, 1
	s_mov_b32 s40, 0
	v_lshl_add_u64 v[6:7], s[28:29], 0, v[130:131]
	v_lshl_add_u64 v[4:5], s[28:29], 0, v[134:135]
	v_lshl_add_u64 v[0:1], s[26:27], 0, v[128:129]
	s_cselect_b64 s[6:7], -1, 0
	s_cmp_lg_u32 s5, 1
	v_lshl_add_u64 v[2:3], s[26:27], 0, v[132:133]
	s_cbranch_scc1 .LBB0_166
	s_barrier

;     __host__ __device__ bool next(int i, Unit& u) const {
;         const long L = (long)i * G + c; if (L >= nwg) return false;
;         int wgid = (int)L; { const int q = nwg / NXCD, r = nwg % NXCD, xcd = wgid % NXCD, off = wgid / NXCD; wgid = (xcd < r ? xcd * (q + 1) : r * (q + 1) + (xcd - r) * q) + off; }
;         const int nig = WGM * nN, gid = wgid / nig, fm = gid * WGM, gsz = (nM - fm) < WGM ? (nM - fm) : WGM;
;         u.pm = fm + ((wgid % nig) % gsz); u.pn = (wgid % nig) / gsz; return true;
;     }
; template <class Epi, class Sched>
; __device__ __forceinline__ void gemm_phase(LAS unsigned char* lds, const Gemm g, const Sched& S, const Epi& E) {
;     ...
;         const bool has_next = S.next(ui + 1, nxt);
;         const char* nA = has_next ? (const char*)g.A + (size_t)nxt.pm * tstepA : cA; const char* nB = has_next ? (const char*)g.Bt + (size_t)nxt.pn * tstepB : cB;
.LBB0_174:
	s_ashr_i32 s16, s18, 3
	s_add_i32 s16, s20, s16
	s_mul_hi_i32 s17, s16, 0xb21642c9
	s_add_i32 s17, s17, s16
	s_lshr_b32 s18, s17, 31
	s_ashr_i32 s17, s17, 7
	s_add_i32 s17, s17, s18
	s_lshl_b32 s18, s17, 2
	s_sub_i32 s19, 0x42, s18
	s_min_i32 s19, s19, 4
	s_abs_i32 s20, s19
	v_cvt_f32_u32_e32 v0, s20
	s_sub_i32 s22, 0, s20
	s_mulk_i32 s17, 0xb8
	s_sub_i32 s17, s16, s17
	v_rcp_iflag_f32_e32 v0, v0
	s_abs_i32 s16, s17
	s_xor_b32 s21, s17, s19
	s_ashr_i32 s21, s21, 31
	v_mul_f32_e32 v0, 0x4f7ffffe, v0
	v_cvt_u32_f32_e32 v0, v0
	s_nop 0
	v_readfirstlane_b32 s23, v0
	s_mul_i32 s22, s22, s23
	s_mul_hi_u32 s22, s23, s22
	s_add_i32 s23, s23, s22
	s_mul_hi_u32 s22, s16, s23
	s_mul_i32 s23, s22, s20
	s_sub_i32 s16, s16, s23
	s_add_i32 s30, s22, 1
	s_sub_i32 s23, s16, s20
	s_cmp_ge_u32 s16, s20
	s_cselect_b32 s22, s30, s22
	s_cselect_b32 s16, s23, s16
	s_add_i32 s23, s22, 1
	s_cmp_ge_u32 s16, s20
	s_cselect_b32 s16, s23, s22
	s_xor_b32 s16, s16, s21
	s_sub_i32 s16, s16, s21
	s_mul_i32 s19, s16, s19
	s_sub_i32 s17, s17, s19
	s_add_i32 s18, s18, s17
